# K-loops restored to baseline text (DMA rebalance and alignment nops dropped: no measured gain); all epilogue/attention/P6 edits kept
# baseline (speedup 1.0000x reference)
; #define PG8_STAGE(bufoff, gbase, voff) do { _Pragma("unroll") for (int _i = 0; _i < 2; ++_i) \
;         __builtin_amdgcn_global_load_lds((const __attribute__((address_space(1))) unsigned*)((const char*)(gbase) + (voff)[_i]), (LAS unsigned*)(lds + (bufoff) + ldsw + _i * 8192), 16, 0, 0); } while (0)
; #define PG8_LDA(dst, b, h) do { _Pragma("unroll") for (int m = 0; m < 4; ++m) _Pragma("unroll") for (int k = 0; k < 2; ++k) dst[m][k] = *(const LAS bf16x8*)(lds + PG8_SA(b, h) + aoff + m * 2048 + k * 1024); } while (0)
; #define PG8_LDB(dst, b, h) do { _Pragma("unroll") for (int n = 0; n < 2; ++n) _Pragma("unroll") for (int k = 0; k < 2; ++k) dst[n][k] = *(const LAS bf16x8*)(lds + PG8_SB(b, h) + boff + n * 2048 + k * 1024); } while (0)
; #define PG8_MMA(ai, bj, At, Bt) do { __builtin_amdgcn_s_setprio(1); _Pragma("unroll") for (int m = 0; m < 4; ++m) _Pragma("unroll") for (int n = 0; n < 2; ++n) _Pragma("unroll") for (int k = 0; k < 2; ++k) \
;         acc[ai][bj][m][n] = __builtin_amdgcn_mfma_f32_16x16x32_bf16(Bt[n][k], At[m][k], acc[ai][bj][m][n], 0, 0, 0); __builtin_amdgcn_s_setprio(0); } while (0)
; #define PG8_WAIT_V(n) asm volatile("s_waitcnt vmcnt(" #n ")" ::: "memory")
; #define PG8_WAIT_L(n) asm volatile("s_waitcnt lgkmcnt(" #n ")" ::: "memory")
; #define PG8_BAR __builtin_amdgcn_s_barrier()
; template <class Epi, class SchedT, bool ALIGN_EPI, bool SP2>
; __device__ __forceinline__ void gemm_phase(LAS unsigned char* lds, const int ldk, const int nt, const SchedT& S, const Epi& E) {
;     ...
;             const bool last = (t == nt - 2);
;             const char* a1 = cA + (size_t)(t + 1) * kstep;
;             const char* a2 = last ? nA : cA + (size_t)(t + 2) * kstep; const char* b2 = last ? nB : cB + (size_t)(t + 2) * kstep;
;             const char* a3 = a2 + kstep; const char* b3 = b2 + kstep;
;             if constexpr (SP2) {
;             PG8_LDB(B0, 0, 0); PG8_LDB(B1, 0, 1); PG8_SCHED; PG8_LDA(At, 0, 0); PG8_STAGE(PG8_SA(1, 1), a1 + hstep, voffA);
;             PG8_WAIT_V(8); PG8_WAIT_L(0); PG8_BAR; PG8_MMA(0, 0, At, B0); PG8_MMA(0, 1, At, B1); PG8_BAR; PG8_SCHED;
;             PG8_LDA(At, 0, 1); PG8_STAGE(PG8_SB(0, 0), b2, voffB); PG8_STAGE(PG8_SB(0, 1), b2 + hstepB, voffB); PG8_STAGE(PG8_SA(0, 0), a2, voffA);
;             PG8_WAIT_V(8); PG8_WAIT_L(0); PG8_BAR; PG8_MMA(1, 0, At, B0); PG8_MMA(1, 1, At, B1); PG8_BAR; PG8_SCHED;
.LBB0_534:
	s_add_u32 s36, s34, 0xfff80080
	s_addc_u32 s37, s35, -1
	s_add_i32 s49, 0, 0x10000
	s_cmp_eq_u32 s47, 12
	s_cselect_b32 s41, s1, s37
	s_cselect_b32 s40, s0, s36
	v_add_u32_e32 v0, s49, v159
	s_cselect_b32 s37, s53, s20
	s_cselect_b32 s36, s52, s17
	s_add_i32 s51, 0, 0x14000
	ds_read_b128 v[144:147], v0
	ds_read_b128 v[148:151], v0 offset:1024
	ds_read_b128 v[152:155], v0 offset:2048
	ds_read_b128 v[174:177], v0 offset:3072
	v_add_u32_e32 v0, s51, v159
	ds_read_b128 v[178:181], v0
	ds_read_b128 v[182:185], v0 offset:1024
	ds_read_b128 v[186:189], v0 offset:2048
	ds_read_b128 v[190:193], v0 offset:3072
	v_lshl_add_u64 v[2:3], s[34:35], 0, v[140:141]
	s_add_i32 m0, s57, 0xc000
	ds_read_b128 v[194:197], v161
	ds_read_b128 v[198:201], v161 offset:1024
	ds_read_b128 v[202:205], v161 offset:2048
	ds_read_b128 v[206:209], v161 offset:3072
	ds_read_b128 v[210:213], v161 offset:4096
	ds_read_b128 v[214:217], v161 offset:5120
	ds_read_b128 v[218:221], v161 offset:6144
	ds_read_b128 v[222:225], v161 offset:7168
	global_load_lds_dwordx4 v[2:3], off
	v_lshl_add_u64 v[2:3], s[34:35], 0, v[142:143]
	s_add_i32 m0, s57, 0xe000
	s_nop 0
	global_load_lds_dwordx4 v[2:3], off
	s_waitcnt vmcnt(8)
	s_waitcnt lgkmcnt(0)
	s_barrier
	s_setprio 1
	s_waitcnt lgkmcnt(0)
	v_mfma_f32_16x16x32_bf16 v[128:131], v[144:147], v[194:197], v[128:131]
	v_mfma_f32_16x16x32_bf16 v[124:127], v[152:155], v[194:197], v[124:127]
	v_mfma_f32_16x16x32_bf16 v[120:123], v[144:147], v[202:205], v[120:123]
	v_mfma_f32_16x16x32_bf16 v[116:119], v[152:155], v[202:205], v[116:119]
	v_mfma_f32_16x16x32_bf16 v[112:115], v[144:147], v[210:213], v[112:115]
	v_mfma_f32_16x16x32_bf16 v[108:111], v[152:155], v[210:213], v[108:111]
	v_mfma_f32_16x16x32_bf16 v[104:107], v[144:147], v[218:221], v[104:107]
	v_mfma_f32_16x16x32_bf16 v[100:103], v[152:155], v[218:221], v[100:103]
	v_mfma_f32_16x16x32_bf16 v[128:131], v[148:151], v[198:201], v[128:131]
	v_mfma_f32_16x16x32_bf16 v[124:127], v[174:177], v[198:201], v[124:127]
	v_mfma_f32_16x16x32_bf16 v[120:123], v[148:151], v[206:209], v[120:123]
	v_mfma_f32_16x16x32_bf16 v[116:119], v[174:177], v[206:209], v[116:119]
	v_mfma_f32_16x16x32_bf16 v[112:115], v[148:151], v[214:217], v[112:115]
	v_mfma_f32_16x16x32_bf16 v[108:111], v[174:177], v[214:217], v[108:111]
	v_mfma_f32_16x16x32_bf16 v[104:107], v[148:151], v[222:225], v[104:107]
	v_mfma_f32_16x16x32_bf16 v[100:103], v[174:177], v[222:225], v[100:103]
	s_setprio 0
	s_setprio 1
	v_mfma_f32_16x16x32_bf16 v[96:99], v[178:181], v[194:197], v[96:99]
	v_mfma_f32_16x16x32_bf16 v[92:95], v[186:189], v[194:197], v[92:95]
	v_mfma_f32_16x16x32_bf16 v[88:91], v[178:181], v[202:205], v[88:91]
	v_mfma_f32_16x16x32_bf16 v[84:87], v[186:189], v[202:205], v[84:87]
	v_mfma_f32_16x16x32_bf16 v[80:83], v[178:181], v[210:213], v[80:83]
	v_mfma_f32_16x16x32_bf16 v[76:79], v[186:189], v[210:213], v[76:79]
	v_mfma_f32_16x16x32_bf16 v[72:75], v[178:181], v[218:221], v[72:75]
	v_mfma_f32_16x16x32_bf16 v[68:71], v[186:189], v[218:221], v[68:71]
	v_mfma_f32_16x16x32_bf16 v[96:99], v[182:185], v[198:201], v[96:99]
	v_mfma_f32_16x16x32_bf16 v[92:95], v[190:193], v[198:201], v[92:95]
	v_mfma_f32_16x16x32_bf16 v[88:91], v[182:185], v[206:209], v[88:91]
	v_mfma_f32_16x16x32_bf16 v[84:87], v[190:193], v[206:209], v[84:87]
	v_mfma_f32_16x16x32_bf16 v[80:83], v[182:185], v[214:217], v[80:83]
	v_mfma_f32_16x16x32_bf16 v[76:79], v[190:193], v[214:217], v[76:79]
	v_mfma_f32_16x16x32_bf16 v[72:75], v[182:185], v[222:225], v[72:75]
	v_mfma_f32_16x16x32_bf16 v[68:71], v[190:193], v[222:225], v[68:71]
	s_setprio 0
	s_barrier
	s_add_i32 s49, s49, s56
	v_lshl_add_u64 v[156:157], s[36:37], 0, v[134:135]
	s_mov_b32 m0, s49
	ds_read_b128 v[194:197], v161 offset:16384
	ds_read_b128 v[198:201], v161 offset:17408
	ds_read_b128 v[202:205], v161 offset:18432
	ds_read_b128 v[206:209], v161 offset:19456
	ds_read_b128 v[210:213], v161 offset:20480
	ds_read_b128 v[214:217], v161 offset:21504
	ds_read_b128 v[218:221], v161 offset:22528
	ds_read_b128 v[222:225], v161 offset:23552
	global_load_lds_dwordx4 v[156:157], off
	s_add_i32 m0, s49, 0x2000
	s_add_u32 s82, s36, 0x20000
	v_lshl_add_u64 v[226:227], s[36:37], 0, v[138:139]
	s_addc_u32 s83, s37, 0
	s_add_i32 s49, s51, s56
	global_load_lds_dwordx4 v[226:227], off
	v_lshl_add_u64 v[2:3], s[82:83], 0, v[134:135]
	s_mov_b32 m0, s49
	v_lshl_add_u64 v[228:229], s[40:41], 0, v[132:133]
	global_load_lds_dwordx4 v[2:3], off
	v_lshl_add_u64 v[2:3], s[82:83], 0, v[138:139]
	s_add_i32 m0, s49, 0x2000
	v_lshl_add_u64 v[230:231], s[40:41], 0, v[136:137]
	global_load_lds_dwordx4 v[2:3], off
	s_mov_b32 m0, s57
	s_nop 0
	global_load_lds_dwordx4 v[228:229], off
	s_mov_b32 m0, s58
	s_nop 0
	global_load_lds_dwordx4 v[230:231], off
	s_waitcnt vmcnt(8)
	s_waitcnt lgkmcnt(0)
	s_barrier
; #define PG8_STAGE(bufoff, gbase, voff) do { _Pragma("unroll") for (int _i = 0; _i < 2; ++_i) \
;         __builtin_amdgcn_global_load_lds((const __attribute__((address_space(1))) unsigned*)((const char*)(gbase) + (voff)[_i]), (LAS unsigned*)(lds + (bufoff) + ldsw + _i * 8192), 16, 0, 0); } while (0)
; #define PG8_LDA(dst, b, h) do { _Pragma("unroll") for (int m = 0; m < 4; ++m) _Pragma("unroll") for (int k = 0; k < 2; ++k) dst[m][k] = *(const LAS bf16x8*)(lds + PG8_SA(b, h) + aoff + m * 2048 + k * 1024); } while (0)
; #define PG8_LDB(dst, b, h) do { _Pragma("unroll") for (int n = 0; n < 2; ++n) _Pragma("unroll") for (int k = 0; k < 2; ++k) dst[n][k] = *(const LAS bf16x8*)(lds + PG8_SB(b, h) + boff + n * 2048 + k * 1024); } while (0)
; #define PG8_MMA(ai, bj, At, Bt) do { __builtin_amdgcn_s_setprio(1); _Pragma("unroll") for (int m = 0; m < 4; ++m) _Pragma("unroll") for (int n = 0; n < 2; ++n) _Pragma("unroll") for (int k = 0; k < 2; ++k) \
;         acc[ai][bj][m][n] = __builtin_amdgcn_mfma_f32_16x16x32_bf16(Bt[n][k], At[m][k], acc[ai][bj][m][n], 0, 0, 0); __builtin_amdgcn_s_setprio(0); } while (0)
; #define PG8_WAIT_V(n) asm volatile("s_waitcnt vmcnt(" #n ")" ::: "memory")
; #define PG8_WAIT_L(n) asm volatile("s_waitcnt lgkmcnt(" #n ")" ::: "memory")
; #define PG8_BAR __builtin_amdgcn_s_barrier()
; #define PG8_SCHED __builtin_amdgcn_sched_barrier(0)
; template <class Epi, class SchedT, bool ALIGN_EPI, bool SP2>
; __device__ __forceinline__ void gemm_phase(LAS unsigned char* lds, const int ldk, const int nt, const SchedT& S, const Epi& E) {
;     ...
;             PG8_LDA(At, 0, 1); PG8_STAGE(PG8_SB(0, 0), b2, voffB); PG8_STAGE(PG8_SB(0, 1), b2 + hstepB, voffB); PG8_STAGE(PG8_SA(0, 0), a2, voffA);
;             PG8_WAIT_V(8); PG8_WAIT_L(0); PG8_BAR; PG8_MMA(1, 0, At, B0); PG8_MMA(1, 1, At, B1); PG8_BAR; PG8_SCHED;
;             PG8_LDB(B0, 1, 0); PG8_LDB(B1, 1, 1); PG8_SCHED; PG8_LDA(At, 1, 0); PG8_STAGE(PG8_SA(0, 1), a2 + hstep, voffA);
;             PG8_WAIT_V(8); PG8_WAIT_L(0); PG8_BAR; PG8_MMA(0, 0, At, B0); PG8_MMA(0, 1, At, B1); PG8_BAR; PG8_SCHED;
	s_setprio 1
	s_waitcnt lgkmcnt(0)
	v_mfma_f32_16x16x32_bf16 v[64:67], v[144:147], v[194:197], v[64:67]
	v_mfma_f32_16x16x32_bf16 v[60:63], v[152:155], v[194:197], v[60:63]
	v_mfma_f32_16x16x32_bf16 v[56:59], v[144:147], v[202:205], v[56:59]
	v_mfma_f32_16x16x32_bf16 v[52:55], v[152:155], v[202:205], v[52:55]
	v_mfma_f32_16x16x32_bf16 v[48:51], v[144:147], v[210:213], v[48:51]
	v_mfma_f32_16x16x32_bf16 v[44:47], v[152:155], v[210:213], v[44:47]
	v_mfma_f32_16x16x32_bf16 v[40:43], v[144:147], v[218:221], v[40:43]
	v_mfma_f32_16x16x32_bf16 v[36:39], v[152:155], v[218:221], v[36:39]
	v_mfma_f32_16x16x32_bf16 v[64:67], v[148:151], v[198:201], v[64:67]
	v_mfma_f32_16x16x32_bf16 v[60:63], v[174:177], v[198:201], v[60:63]
	v_mfma_f32_16x16x32_bf16 v[56:59], v[148:151], v[206:209], v[56:59]
	v_mfma_f32_16x16x32_bf16 v[52:55], v[174:177], v[206:209], v[52:55]
	v_mfma_f32_16x16x32_bf16 v[48:51], v[148:151], v[214:217], v[48:51]
	v_mfma_f32_16x16x32_bf16 v[44:47], v[174:177], v[214:217], v[44:47]
	v_mfma_f32_16x16x32_bf16 v[40:43], v[148:151], v[222:225], v[40:43]
	v_mfma_f32_16x16x32_bf16 v[36:39], v[174:177], v[222:225], v[36:39]
	s_setprio 0
	s_setprio 1
	v_mfma_f32_16x16x32_bf16 v[32:35], v[178:181], v[194:197], v[32:35]
	v_mfma_f32_16x16x32_bf16 v[28:31], v[186:189], v[194:197], v[28:31]
	v_mfma_f32_16x16x32_bf16 v[24:27], v[178:181], v[202:205], v[24:27]
	v_mfma_f32_16x16x32_bf16 v[20:23], v[186:189], v[202:205], v[20:23]
	v_mfma_f32_16x16x32_bf16 v[16:19], v[178:181], v[210:213], v[16:19]
	v_mfma_f32_16x16x32_bf16 v[12:15], v[186:189], v[210:213], v[12:15]
	v_mfma_f32_16x16x32_bf16 v[8:11], v[178:181], v[218:221], v[8:11]
	v_mfma_f32_16x16x32_bf16 v[2:5], v[186:189], v[218:221], v[4:7]
	v_mfma_f32_16x16x32_bf16 v[32:35], v[182:185], v[198:201], v[32:35]
	v_mfma_f32_16x16x32_bf16 v[28:31], v[190:193], v[198:201], v[28:31]
	v_mfma_f32_16x16x32_bf16 v[24:27], v[182:185], v[206:209], v[24:27]
	v_mfma_f32_16x16x32_bf16 v[20:23], v[190:193], v[206:209], v[20:23]
	v_mfma_f32_16x16x32_bf16 v[16:19], v[182:185], v[214:217], v[16:19]
	v_mfma_f32_16x16x32_bf16 v[12:15], v[190:193], v[214:217], v[12:15]
	v_mfma_f32_16x16x32_bf16 v[8:11], v[182:185], v[222:225], v[8:11]
	v_mfma_f32_16x16x32_bf16 v[2:5], v[190:193], v[222:225], v[2:5]
	s_setprio 0
	s_barrier
	s_add_i32 s49, 0, 0x18000
	v_add_u32_e32 v0, s49, v159
	s_add_i32 s51, 0, 0x1c000
	ds_read_b128 v[144:147], v0
	ds_read_b128 v[148:151], v0 offset:1024
	ds_read_b128 v[152:155], v0 offset:2048
	ds_read_b128 v[174:177], v0 offset:3072
	v_add_u32_e32 v0, s51, v159
	ds_read_b128 v[178:181], v0
	ds_read_b128 v[182:185], v0 offset:1024
	ds_read_b128 v[186:189], v0 offset:2048
	ds_read_b128 v[190:193], v0 offset:3072
	s_add_u32 s40, s40, 0x80000
	s_addc_u32 s41, s41, 0
	s_mov_b32 m0, s59
	v_lshl_add_u64 v[6:7], s[40:41], 0, v[132:133]
	ds_read_b128 v[194:197], v161 offset:32768
	ds_read_b128 v[198:201], v161 offset:33792
	ds_read_b128 v[202:205], v161 offset:34816
	ds_read_b128 v[206:209], v161 offset:35840
	ds_read_b128 v[210:213], v161 offset:36864
	ds_read_b128 v[214:217], v161 offset:37888
	ds_read_b128 v[218:221], v161 offset:38912
	ds_read_b128 v[222:225], v161 offset:39936
	global_load_lds_dwordx4 v[6:7], off
	v_lshl_add_u64 v[6:7], s[40:41], 0, v[136:137]
	s_mov_b32 m0, s60
	s_nop 0
	global_load_lds_dwordx4 v[6:7], off
	s_waitcnt vmcnt(8)
	s_waitcnt lgkmcnt(0)
	s_barrier
	s_setprio 1
	s_waitcnt lgkmcnt(0)
	v_mfma_f32_16x16x32_bf16 v[128:131], v[144:147], v[194:197], v[128:131]
	v_mfma_f32_16x16x32_bf16 v[124:127], v[152:155], v[194:197], v[124:127]
	v_mfma_f32_16x16x32_bf16 v[120:123], v[144:147], v[202:205], v[120:123]
	v_mfma_f32_16x16x32_bf16 v[116:119], v[152:155], v[202:205], v[116:119]
	v_mfma_f32_16x16x32_bf16 v[112:115], v[144:147], v[210:213], v[112:115]
	v_mfma_f32_16x16x32_bf16 v[108:111], v[152:155], v[210:213], v[108:111]
	v_mfma_f32_16x16x32_bf16 v[104:107], v[144:147], v[218:221], v[104:107]
	v_mfma_f32_16x16x32_bf16 v[100:103], v[152:155], v[218:221], v[100:103]
	v_mfma_f32_16x16x32_bf16 v[128:131], v[148:151], v[198:201], v[128:131]
	v_mfma_f32_16x16x32_bf16 v[124:127], v[174:177], v[198:201], v[124:127]
	v_mfma_f32_16x16x32_bf16 v[120:123], v[148:151], v[206:209], v[120:123]
	v_mfma_f32_16x16x32_bf16 v[116:119], v[174:177], v[206:209], v[116:119]
	v_mfma_f32_16x16x32_bf16 v[112:115], v[148:151], v[214:217], v[112:115]
	v_mfma_f32_16x16x32_bf16 v[108:111], v[174:177], v[214:217], v[108:111]
	v_mfma_f32_16x16x32_bf16 v[104:107], v[148:151], v[222:225], v[104:107]
	v_mfma_f32_16x16x32_bf16 v[100:103], v[174:177], v[222:225], v[100:103]
	s_setprio 0
	s_setprio 1
	v_mfma_f32_16x16x32_bf16 v[96:99], v[178:181], v[194:197], v[96:99]
	v_mfma_f32_16x16x32_bf16 v[92:95], v[186:189], v[194:197], v[92:95]
	v_mfma_f32_16x16x32_bf16 v[88:91], v[178:181], v[202:205], v[88:91]
	v_mfma_f32_16x16x32_bf16 v[84:87], v[186:189], v[202:205], v[84:87]
	v_mfma_f32_16x16x32_bf16 v[80:83], v[178:181], v[210:213], v[80:83]
	v_mfma_f32_16x16x32_bf16 v[76:79], v[186:189], v[210:213], v[76:79]
	v_mfma_f32_16x16x32_bf16 v[72:75], v[178:181], v[218:221], v[72:75]
	v_mfma_f32_16x16x32_bf16 v[68:71], v[186:189], v[218:221], v[68:71]
	v_mfma_f32_16x16x32_bf16 v[96:99], v[182:185], v[198:201], v[96:99]
	v_mfma_f32_16x16x32_bf16 v[92:95], v[190:193], v[198:201], v[92:95]
	v_mfma_f32_16x16x32_bf16 v[88:91], v[182:185], v[206:209], v[88:91]
	v_mfma_f32_16x16x32_bf16 v[84:87], v[190:193], v[206:209], v[84:87]
	v_mfma_f32_16x16x32_bf16 v[80:83], v[182:185], v[214:217], v[80:83]
	v_mfma_f32_16x16x32_bf16 v[76:79], v[190:193], v[214:217], v[76:79]
	v_mfma_f32_16x16x32_bf16 v[72:75], v[182:185], v[222:225], v[72:75]
	v_mfma_f32_16x16x32_bf16 v[68:71], v[190:193], v[222:225], v[68:71]
	s_setprio 0
	s_barrier
; #define PG8_STAGE(bufoff, gbase, voff) do { _Pragma("unroll") for (int _i = 0; _i < 2; ++_i) \
;         __builtin_amdgcn_global_load_lds((const __attribute__((address_space(1))) unsigned*)((const char*)(gbase) + (voff)[_i]), (LAS unsigned*)(lds + (bufoff) + ldsw + _i * 8192), 16, 0, 0); } while (0)
; #define PG8_LDA(dst, b, h) do { _Pragma("unroll") for (int m = 0; m < 4; ++m) _Pragma("unroll") for (int k = 0; k < 2; ++k) dst[m][k] = *(const LAS bf16x8*)(lds + PG8_SA(b, h) + aoff + m * 2048 + k * 1024); } while (0)
; #define PG8_MMA(ai, bj, At, Bt) do { __builtin_amdgcn_s_setprio(1); _Pragma("unroll") for (int m = 0; m < 4; ++m) _Pragma("unroll") for (int n = 0; n < 2; ++n) _Pragma("unroll") for (int k = 0; k < 2; ++k) \
;         acc[ai][bj][m][n] = __builtin_amdgcn_mfma_f32_16x16x32_bf16(Bt[n][k], At[m][k], acc[ai][bj][m][n], 0, 0, 0); __builtin_amdgcn_s_setprio(0); } while (0)
; #define PG8_WAIT_V(n) asm volatile("s_waitcnt vmcnt(" #n ")" ::: "memory")
; #define PG8_WAIT_L(n) asm volatile("s_waitcnt lgkmcnt(" #n ")" ::: "memory")
; template <class Epi, class SchedT, bool ALIGN_EPI, bool SP2>
; __device__ __forceinline__ void gemm_phase(LAS unsigned char* lds, const int ldk, const int nt, const SchedT& S, const Epi& E) {
;     ...
;             PG8_LDA(At, 1, 1); PG8_STAGE(PG8_SB(1, 0), b3, voffB); PG8_STAGE(PG8_SB(1, 1), b3 + hstepB, voffB); PG8_STAGE(PG8_SA(1, 0), a3, voffA);
;             PG8_WAIT_V(8); PG8_WAIT_L(0); PG8_BAR; PG8_MMA(1, 0, At, B0); PG8_MMA(1, 1, At, B1); PG8_BAR; PG8_SCHED;
;     __device__ __forceinline__ void operator()(f32x4 (&acc)[2][2][4][2], const Unit& u, int wr, int wc, int fr, int fq) const {
;         const int row0 = u.pm * BM + wr * 64 + fr, col0 = u.pn * BM + wc * 64 + 8 * fq;
; #pragma unroll
;         for (int ai = 0; ai < 2; ++ai)
; #pragma unroll
;             for (int m = 0; m < 4; ++m) {
;                 const int row = row0 + ai * HALF + m * 16;
; #pragma unroll
;                 for (int bj = 0; bj < 2; ++bj) {
;                     const int col = col0 + bj * 32;
;                     const unsigned char* grow = (const unsigned char*)Gt + (size_t)row * 4096 + col;
;                     const u32x2 gw = *(const u32x2*)(grow + 2048);
;                     f32x4 g0 = gate_d4(gw.x), g1 = gate_d4(gw.y);
;                     if (u.kind == 0) {
;                         const u32x2 aw = *(const u32x2*)grow;
	s_add_i32 s40, s49, s56
	v_lshl_add_u64 v[6:7], v[156:157], 0, s[24:25]
	s_mov_b32 m0, s40
	ds_read_b128 v[194:197], v161 offset:49152
	ds_read_b128 v[198:201], v161 offset:50176
	ds_read_b128 v[202:205], v161 offset:51200
	ds_read_b128 v[206:209], v161 offset:52224
	ds_read_b128 v[210:213], v161 offset:53248
	ds_read_b128 v[214:217], v161 offset:54272
	ds_read_b128 v[218:221], v161 offset:55296
	ds_read_b128 v[222:225], v161 offset:56320
	global_load_lds_dwordx4 v[6:7], off
	s_add_i32 m0, s40, 0x2000
	s_add_u32 s36, s36, 0x20080
	v_lshl_add_u64 v[6:7], v[226:227], 0, s[24:25]
	s_addc_u32 s37, s37, 0
	s_add_i32 s40, s51, s56
	global_load_lds_dwordx4 v[6:7], off
	v_lshl_add_u64 v[6:7], s[36:37], 0, v[134:135]
	s_mov_b32 m0, s40
	s_nop 0
	global_load_lds_dwordx4 v[6:7], off
	v_lshl_add_u64 v[6:7], s[36:37], 0, v[138:139]
	s_add_i32 m0, s40, 0x2000
	s_nop 0
	global_load_lds_dwordx4 v[6:7], off
	v_lshl_add_u64 v[6:7], v[228:229], 0, s[24:25]
	s_mov_b32 m0, s61
	s_nop 0
	global_load_lds_dwordx4 v[6:7], off
	v_lshl_add_u64 v[6:7], v[230:231], 0, s[24:25]
	s_mov_b32 m0, s62
	s_nop 0
	global_load_lds_dwordx4 v[6:7], off
	s_waitcnt vmcnt(8)
	s_waitcnt lgkmcnt(0)
	s_barrier
	s_setprio 1
	s_waitcnt lgkmcnt(0)
	v_mfma_f32_16x16x32_bf16 v[64:67], v[144:147], v[194:197], v[64:67]
	v_mfma_f32_16x16x32_bf16 v[60:63], v[152:155], v[194:197], v[60:63]
	v_mfma_f32_16x16x32_bf16 v[56:59], v[144:147], v[202:205], v[56:59]
	v_mfma_f32_16x16x32_bf16 v[52:55], v[152:155], v[202:205], v[52:55]
	v_mfma_f32_16x16x32_bf16 v[48:51], v[144:147], v[210:213], v[48:51]
	v_mfma_f32_16x16x32_bf16 v[44:47], v[152:155], v[210:213], v[44:47]
	v_mfma_f32_16x16x32_bf16 v[40:43], v[144:147], v[218:221], v[40:43]
	v_mfma_f32_16x16x32_bf16 v[36:39], v[152:155], v[218:221], v[36:39]
	v_mfma_f32_16x16x32_bf16 v[64:67], v[148:151], v[198:201], v[64:67]
	v_mfma_f32_16x16x32_bf16 v[60:63], v[174:177], v[198:201], v[60:63]
	v_mfma_f32_16x16x32_bf16 v[56:59], v[148:151], v[206:209], v[56:59]
	v_mfma_f32_16x16x32_bf16 v[52:55], v[174:177], v[206:209], v[52:55]
	v_mfma_f32_16x16x32_bf16 v[48:51], v[148:151], v[214:217], v[48:51]
	v_mfma_f32_16x16x32_bf16 v[44:47], v[174:177], v[214:217], v[44:47]
	v_mfma_f32_16x16x32_bf16 v[40:43], v[148:151], v[222:225], v[40:43]
	v_mfma_f32_16x16x32_bf16 v[36:39], v[174:177], v[222:225], v[36:39]
	s_setprio 0
	s_setprio 1
	v_mfma_f32_16x16x32_bf16 v[32:35], v[178:181], v[194:197], v[32:35]
	v_mfma_f32_16x16x32_bf16 v[28:31], v[186:189], v[194:197], v[28:31]
	v_mfma_f32_16x16x32_bf16 v[24:27], v[178:181], v[202:205], v[24:27]
	v_mfma_f32_16x16x32_bf16 v[20:23], v[186:189], v[202:205], v[20:23]
	v_mfma_f32_16x16x32_bf16 v[16:19], v[178:181], v[210:213], v[16:19]
	v_mfma_f32_16x16x32_bf16 v[12:15], v[186:189], v[210:213], v[12:15]
	v_mfma_f32_16x16x32_bf16 v[6:9], v[178:181], v[218:221], v[8:11]
	v_mfma_f32_16x16x32_bf16 v[2:5], v[186:189], v[218:221], v[2:5]
	v_mfma_f32_16x16x32_bf16 v[32:35], v[182:185], v[198:201], v[32:35]
	v_mfma_f32_16x16x32_bf16 v[28:31], v[190:193], v[198:201], v[28:31]
	v_mfma_f32_16x16x32_bf16 v[24:27], v[182:185], v[206:209], v[24:27]
	v_mfma_f32_16x16x32_bf16 v[20:23], v[190:193], v[206:209], v[20:23]
	v_mfma_f32_16x16x32_bf16 v[16:19], v[182:185], v[214:217], v[16:19]
	v_mfma_f32_16x16x32_bf16 v[12:15], v[190:193], v[214:217], v[12:15]
	v_mfma_f32_16x16x32_bf16 v[8:11], v[182:185], v[222:225], v[6:9]
	v_mfma_f32_16x16x32_bf16 v[4:7], v[190:193], v[222:225], v[2:5]
	s_setprio 0
	s_barrier
	s_add_i32 s47, s47, 2
	s_add_u32 s34, s34, 0x100
	s_addc_u32 s35, s35, 0
	s_add_u32 s17, s17, 0x100
	s_addc_u32 s20, s20, 0
	s_cmp_gt_u32 s47, 13
	s_cbranch_scc0 .LBB0_534
	v_lshl_add_u32 v144, s16, 8, v158
	v_lshl_or_b32 v145, s12, 8, v160
	v_lshl_add_u32 v146, v144, 12, v145
	v_add_u32_e32 v147, 0x10000, v146
	v_add_u32_e32 v148, 0x20000, v146
	v_add_u32_e32 v149, 0x30000, v146
	v_add_u32_e32 v150, 0x80000, v146
	v_add_u32_e32 v151, 0x90000, v146
	v_add_u32_e32 v152, 0xa0000, v146
	v_add_u32_e32 v153, 0xb0000, v146
	s_cmp_lg_u32 s13, 0
	s_cbranch_scc1 .Lp3e_k1_loads
	global_load_dwordx2 v[174:175], v146, s[30:31] offset:2048
	global_load_dwordx2 v[176:177], v146, s[30:31] offset:0
	global_load_dwordx2 v[178:179], v146, s[30:31] offset:2080
	global_load_dwordx2 v[180:181], v146, s[30:31] offset:32
	global_load_dwordx2 v[182:183], v147, s[30:31] offset:2048
	global_load_dwordx2 v[184:185], v147, s[30:31] offset:0
	global_load_dwordx2 v[186:187], v147, s[30:31] offset:2080
	global_load_dwordx2 v[188:189], v147, s[30:31] offset:32
	global_load_dwordx2 v[190:191], v148, s[30:31] offset:2048
	global_load_dwordx2 v[192:193], v148, s[30:31] offset:0
	global_load_dwordx2 v[194:195], v148, s[30:31] offset:2080
	global_load_dwordx2 v[196:197], v148, s[30:31] offset:32
	global_load_dwordx2 v[198:199], v149, s[30:31] offset:2048
	global_load_dwordx2 v[200:201], v149, s[30:31] offset:0
	global_load_dwordx2 v[202:203], v149, s[30:31] offset:2080
	global_load_dwordx2 v[204:205], v149, s[30:31] offset:32
	global_load_dwordx2 v[206:207], v150, s[30:31] offset:2048
	global_load_dwordx2 v[208:209], v150, s[30:31] offset:0
	global_load_dwordx2 v[210:211], v150, s[30:31] offset:2080
	global_load_dwordx2 v[212:213], v150, s[30:31] offset:32
	global_load_dwordx2 v[214:215], v151, s[30:31] offset:2048
	global_load_dwordx2 v[216:217], v151, s[30:31] offset:0
	global_load_dwordx2 v[218:219], v151, s[30:31] offset:2080
	global_load_dwordx2 v[220:221], v151, s[30:31] offset:32
	global_load_dwordx2 v[222:223], v152, s[30:31] offset:2048
	global_load_dwordx2 v[224:225], v152, s[30:31] offset:0
	global_load_dwordx2 v[226:227], v152, s[30:31] offset:2080
	global_load_dwordx2 v[228:229], v152, s[30:31] offset:32
	global_load_dwordx2 v[230:231], v153, s[30:31] offset:2048
	global_load_dwordx2 v[232:233], v153, s[30:31] offset:0
	global_load_dwordx2 v[234:235], v153, s[30:31] offset:2080
	global_load_dwordx2 v[236:237], v153, s[30:31] offset:32
	s_branch .Lp3e_align

; #define PG8_STAGE(bufoff, gbase, voff) do { _Pragma("unroll") for (int _i = 0; _i < 2; ++_i) \
;         __builtin_amdgcn_global_load_lds((const __attribute__((address_space(1))) unsigned*)((const char*)(gbase) + (voff)[_i]), (LAS unsigned*)(lds + (bufoff) + ldsw + _i * 8192), 16, 0, 0); } while (0)
; #define PG8_LDA(dst, b, h) do { _Pragma("unroll") for (int m = 0; m < 4; ++m) _Pragma("unroll") for (int k = 0; k < 2; ++k) dst[m][k] = *(const LAS bf16x8*)(lds + PG8_SA(b, h) + aoff + m * 2048 + k * 1024); } while (0)
; #define PG8_LDB(dst, b, h) do { _Pragma("unroll") for (int n = 0; n < 2; ++n) _Pragma("unroll") for (int k = 0; k < 2; ++k) dst[n][k] = *(const LAS bf16x8*)(lds + PG8_SB(b, h) + boff + n * 2048 + k * 1024); } while (0)
; #define PG8_MMA(ai, bj, At, Bt) do { __builtin_amdgcn_s_setprio(1); _Pragma("unroll") for (int m = 0; m < 4; ++m) _Pragma("unroll") for (int n = 0; n < 2; ++n) _Pragma("unroll") for (int k = 0; k < 2; ++k) \
;         acc[ai][bj][m][n] = __builtin_amdgcn_mfma_f32_16x16x32_bf16(Bt[n][k], At[m][k], acc[ai][bj][m][n], 0, 0, 0); __builtin_amdgcn_s_setprio(0); } while (0)
; #define PG8_WAIT_V(n) asm volatile("s_waitcnt vmcnt(" #n ")" ::: "memory")
; #define PG8_WAIT_L(n) asm volatile("s_waitcnt lgkmcnt(" #n ")" ::: "memory")
; #define PG8_BAR __builtin_amdgcn_s_barrier()
; template <class Epi, class SchedT, bool ALIGN_EPI, bool SP2>
; __device__ __forceinline__ void gemm_phase(LAS unsigned char* lds, const int ldk, const int nt, const SchedT& S, const Epi& E) {
;     ...
;             const bool last = (t == nt - 2);
;             const char* a1 = cA + (size_t)(t + 1) * kstep;
;             const char* a2 = last ? nA : cA + (size_t)(t + 2) * kstep; const char* b2 = last ? nB : cB + (size_t)(t + 2) * kstep;
;             const char* a3 = a2 + kstep; const char* b3 = b2 + kstep;
;             if constexpr (SP2) {
;             PG8_LDB(B0, 0, 0); PG8_LDB(B1, 0, 1); PG8_SCHED; PG8_LDA(At, 0, 0); PG8_STAGE(PG8_SA(1, 1), a1 + hstep, voffA);
;             PG8_WAIT_V(8); PG8_WAIT_L(0); PG8_BAR; PG8_MMA(0, 0, At, B0); PG8_MMA(0, 1, At, B1); PG8_BAR; PG8_SCHED;
;             PG8_LDA(At, 0, 1); PG8_STAGE(PG8_SB(0, 0), b2, voffB); PG8_STAGE(PG8_SB(0, 1), b2 + hstepB, voffB); PG8_STAGE(PG8_SA(0, 0), a2, voffA);
;             PG8_WAIT_V(8); PG8_WAIT_L(0); PG8_BAR; PG8_MMA(1, 0, At, B0); PG8_MMA(1, 1, At, B1); PG8_BAR; PG8_SCHED;
.LBB0_752:
	s_add_u32 s36, s34, 0xfff80080
	s_addc_u32 s37, s35, -1
	s_add_i32 s61, 0, 0x10000
	s_cmp_eq_u32 s59, 28
	s_cselect_b32 vcc_hi, s1, s37
	s_cselect_b32 vcc_lo, s0, s36
	s_cselect_b32 s37, s63, s17
	s_cselect_b32 s36, s62, s13
	s_add_i32 s64, 0, 0x14000
	v_add_u32_e32 v142, s61, v248
	v_add_u32_e32 v182, s64, v248
	ds_read_b128 v[130:133], v142
	ds_read_b128 v[134:137], v142 offset:1024
	ds_read_b128 v[138:141], v142 offset:2048
	ds_read_b128 v[142:145], v142 offset:3072
	ds_read_b128 v[158:161], v182
	ds_read_b128 v[174:177], v182 offset:1024
	ds_read_b128 v[178:181], v182 offset:2048
	ds_read_b128 v[182:185], v182 offset:3072
	v_lshl_add_u64 v[218:219], s[34:35], 0, v[154:155]
	s_add_i32 m0, s85, 0xc000
	ds_read_b128 v[186:189], v251
	ds_read_b128 v[190:193], v251 offset:1024
	ds_read_b128 v[194:197], v251 offset:2048
	ds_read_b128 v[198:201], v251 offset:3072
	ds_read_b128 v[202:205], v251 offset:4096
	ds_read_b128 v[206:209], v251 offset:5120
	ds_read_b128 v[210:213], v251 offset:6144
	ds_read_b128 v[214:217], v251 offset:7168
	global_load_lds_dwordx4 v[218:219], off
	v_lshl_add_u64 v[218:219], s[34:35], 0, v[156:157]
	s_add_i32 m0, s85, 0xe000
	s_nop 0
	global_load_lds_dwordx4 v[218:219], off
	s_waitcnt vmcnt(8)
	s_waitcnt lgkmcnt(0)
	s_barrier
	s_setprio 1
	s_waitcnt lgkmcnt(0)
	v_mfma_f32_16x16x32_bf16 v[126:129], v[130:133], v[186:189], v[126:129]
	v_mfma_f32_16x16x32_bf16 v[62:65], v[138:141], v[186:189], v[62:65]
	v_mfma_f32_16x16x32_bf16 v[118:121], v[130:133], v[194:197], v[118:121]
	v_mfma_f32_16x16x32_bf16 v[58:61], v[138:141], v[194:197], v[58:61]
	v_mfma_f32_16x16x32_bf16 v[110:113], v[130:133], v[202:205], v[110:113]
	v_mfma_f32_16x16x32_bf16 v[46:49], v[138:141], v[202:205], v[46:49]
	v_mfma_f32_16x16x32_bf16 v[106:109], v[130:133], v[210:213], v[106:109]
	v_mfma_f32_16x16x32_bf16 v[42:45], v[138:141], v[210:213], v[42:45]
	v_mfma_f32_16x16x32_bf16 v[126:129], v[134:137], v[190:193], v[126:129]
	v_mfma_f32_16x16x32_bf16 v[62:65], v[142:145], v[190:193], v[62:65]
	v_mfma_f32_16x16x32_bf16 v[118:121], v[134:137], v[198:201], v[118:121]
	v_mfma_f32_16x16x32_bf16 v[58:61], v[142:145], v[198:201], v[58:61]
	v_mfma_f32_16x16x32_bf16 v[110:113], v[134:137], v[206:209], v[110:113]
	v_mfma_f32_16x16x32_bf16 v[46:49], v[142:145], v[206:209], v[46:49]
	v_mfma_f32_16x16x32_bf16 v[106:109], v[134:137], v[214:217], v[106:109]
	v_mfma_f32_16x16x32_bf16 v[42:45], v[142:145], v[214:217], v[42:45]
	s_setprio 0
	s_setprio 1
	v_mfma_f32_16x16x32_bf16 v[122:125], v[158:161], v[186:189], v[122:125]
	v_mfma_f32_16x16x32_bf16 v[54:57], v[178:181], v[186:189], v[54:57]
	v_mfma_f32_16x16x32_bf16 v[114:117], v[158:161], v[194:197], v[114:117]
	v_mfma_f32_16x16x32_bf16 v[50:53], v[178:181], v[194:197], v[50:53]
	v_mfma_f32_16x16x32_bf16 v[102:105], v[158:161], v[202:205], v[102:105]
	v_mfma_f32_16x16x32_bf16 v[38:41], v[178:181], v[202:205], v[38:41]
	v_mfma_f32_16x16x32_bf16 v[98:101], v[158:161], v[210:213], v[98:101]
	v_mfma_f32_16x16x32_bf16 v[34:37], v[178:181], v[210:213], v[34:37]
	v_mfma_f32_16x16x32_bf16 v[122:125], v[174:177], v[190:193], v[122:125]
	v_mfma_f32_16x16x32_bf16 v[54:57], v[182:185], v[190:193], v[54:57]
	v_mfma_f32_16x16x32_bf16 v[114:117], v[174:177], v[198:201], v[114:117]
	v_mfma_f32_16x16x32_bf16 v[50:53], v[182:185], v[198:201], v[50:53]
	v_mfma_f32_16x16x32_bf16 v[102:105], v[174:177], v[206:209], v[102:105]
	v_mfma_f32_16x16x32_bf16 v[38:41], v[182:185], v[206:209], v[38:41]
	v_mfma_f32_16x16x32_bf16 v[98:101], v[174:177], v[214:217], v[98:101]
	v_mfma_f32_16x16x32_bf16 v[34:37], v[182:185], v[214:217], v[34:37]
	s_setprio 0
	s_barrier
	s_add_i32 s61, s61, s84
	v_lshl_add_u64 v[218:219], s[36:37], 0, v[0:1]
	s_mov_b32 m0, s61
	ds_read_b128 v[186:189], v251 offset:16384
	ds_read_b128 v[190:193], v251 offset:17408
	ds_read_b128 v[194:197], v251 offset:18432
	ds_read_b128 v[198:201], v251 offset:19456
	ds_read_b128 v[202:205], v251 offset:20480
	ds_read_b128 v[206:209], v251 offset:21504
	ds_read_b128 v[210:213], v251 offset:22528
	ds_read_b128 v[214:217], v251 offset:23552
	global_load_lds_dwordx4 v[218:219], off
	s_add_i32 m0, s61, 0x2000
	s_add_u32 s94, s36, 0x20000
	v_lshl_add_u64 v[220:221], s[36:37], 0, v[150:151]
	s_addc_u32 s95, s37, 0
	s_add_i32 s61, s64, s84
	global_load_lds_dwordx4 v[220:221], off
	v_lshl_add_u64 v[222:223], s[94:95], 0, v[0:1]
	s_mov_b32 m0, s61
	v_lshl_add_u64 v[224:225], vcc, 0, v[148:149]
	global_load_lds_dwordx4 v[222:223], off
	v_lshl_add_u64 v[222:223], s[94:95], 0, v[150:151]
	s_add_i32 m0, s61, 0x2000
	s_nop 0
	global_load_lds_dwordx4 v[222:223], off
	v_lshl_add_u64 v[222:223], vcc, 0, v[146:147]
	s_mov_b32 m0, s85
	s_nop 0
	global_load_lds_dwordx4 v[222:223], off
	s_mov_b32 m0, s86
	s_nop 0
	global_load_lds_dwordx4 v[224:225], off
	s_waitcnt vmcnt(8)
	s_waitcnt lgkmcnt(0)
	s_barrier
; #define PG8_STAGE(bufoff, gbase, voff) do { _Pragma("unroll") for (int _i = 0; _i < 2; ++_i) \
;         __builtin_amdgcn_global_load_lds((const __attribute__((address_space(1))) unsigned*)((const char*)(gbase) + (voff)[_i]), (LAS unsigned*)(lds + (bufoff) + ldsw + _i * 8192), 16, 0, 0); } while (0)
; #define PG8_LDA(dst, b, h) do { _Pragma("unroll") for (int m = 0; m < 4; ++m) _Pragma("unroll") for (int k = 0; k < 2; ++k) dst[m][k] = *(const LAS bf16x8*)(lds + PG8_SA(b, h) + aoff + m * 2048 + k * 1024); } while (0)
; #define PG8_LDB(dst, b, h) do { _Pragma("unroll") for (int n = 0; n < 2; ++n) _Pragma("unroll") for (int k = 0; k < 2; ++k) dst[n][k] = *(const LAS bf16x8*)(lds + PG8_SB(b, h) + boff + n * 2048 + k * 1024); } while (0)
; #define PG8_MMA(ai, bj, At, Bt) do { __builtin_amdgcn_s_setprio(1); _Pragma("unroll") for (int m = 0; m < 4; ++m) _Pragma("unroll") for (int n = 0; n < 2; ++n) _Pragma("unroll") for (int k = 0; k < 2; ++k) \
;         acc[ai][bj][m][n] = __builtin_amdgcn_mfma_f32_16x16x32_bf16(Bt[n][k], At[m][k], acc[ai][bj][m][n], 0, 0, 0); __builtin_amdgcn_s_setprio(0); } while (0)
; #define PG8_WAIT_V(n) asm volatile("s_waitcnt vmcnt(" #n ")" ::: "memory")
; #define PG8_WAIT_L(n) asm volatile("s_waitcnt lgkmcnt(" #n ")" ::: "memory")
; #define PG8_BAR __builtin_amdgcn_s_barrier()
; #define PG8_SCHED __builtin_amdgcn_sched_barrier(0)
; template <class Epi, class SchedT, bool ALIGN_EPI, bool SP2>
; __device__ __forceinline__ void gemm_phase(LAS unsigned char* lds, const int ldk, const int nt, const SchedT& S, const Epi& E) {
;     ...
;             PG8_LDA(At, 0, 1); PG8_STAGE(PG8_SB(0, 0), b2, voffB); PG8_STAGE(PG8_SB(0, 1), b2 + hstepB, voffB); PG8_STAGE(PG8_SA(0, 0), a2, voffA);
;             PG8_WAIT_V(8); PG8_WAIT_L(0); PG8_BAR; PG8_MMA(1, 0, At, B0); PG8_MMA(1, 1, At, B1); PG8_BAR; PG8_SCHED;
;             PG8_LDB(B0, 1, 0); PG8_LDB(B1, 1, 1); PG8_SCHED; PG8_LDA(At, 1, 0); PG8_STAGE(PG8_SA(0, 1), a2 + hstep, voffA);
;             PG8_WAIT_V(8); PG8_WAIT_L(0); PG8_BAR; PG8_MMA(0, 0, At, B0); PG8_MMA(0, 1, At, B1); PG8_BAR; PG8_SCHED;
	s_setprio 1
	s_waitcnt lgkmcnt(0)
	v_mfma_f32_16x16x32_bf16 v[94:97], v[130:133], v[186:189], v[94:97]
	v_mfma_f32_16x16x32_bf16 v[30:33], v[138:141], v[186:189], v[30:33]
	v_mfma_f32_16x16x32_bf16 v[90:93], v[130:133], v[194:197], v[90:93]
	v_mfma_f32_16x16x32_bf16 v[26:29], v[138:141], v[194:197], v[26:29]
	v_mfma_f32_16x16x32_bf16 v[78:81], v[130:133], v[202:205], v[78:81]
	v_mfma_f32_16x16x32_bf16 v[14:17], v[138:141], v[202:205], v[14:17]
	v_mfma_f32_16x16x32_bf16 v[74:77], v[130:133], v[210:213], v[74:77]
	v_mfma_f32_16x16x32_bf16 v[10:13], v[138:141], v[210:213], v[10:13]
	v_mfma_f32_16x16x32_bf16 v[94:97], v[134:137], v[190:193], v[94:97]
	v_mfma_f32_16x16x32_bf16 v[30:33], v[142:145], v[190:193], v[30:33]
	v_mfma_f32_16x16x32_bf16 v[90:93], v[134:137], v[198:201], v[90:93]
	v_mfma_f32_16x16x32_bf16 v[26:29], v[142:145], v[198:201], v[26:29]
	v_mfma_f32_16x16x32_bf16 v[78:81], v[134:137], v[206:209], v[78:81]
	v_mfma_f32_16x16x32_bf16 v[14:17], v[142:145], v[206:209], v[14:17]
	v_mfma_f32_16x16x32_bf16 v[74:77], v[134:137], v[214:217], v[74:77]
	v_mfma_f32_16x16x32_bf16 v[10:13], v[142:145], v[214:217], v[10:13]
	s_setprio 0
	s_setprio 1
	v_mfma_f32_16x16x32_bf16 v[86:89], v[158:161], v[186:189], v[86:89]
	v_mfma_f32_16x16x32_bf16 v[22:25], v[178:181], v[186:189], v[22:25]
	v_mfma_f32_16x16x32_bf16 v[82:85], v[158:161], v[194:197], v[82:85]
	v_mfma_f32_16x16x32_bf16 v[18:21], v[178:181], v[194:197], v[18:21]
	v_mfma_f32_16x16x32_bf16 v[70:73], v[158:161], v[202:205], v[70:73]
	v_mfma_f32_16x16x32_bf16 v[6:9], v[178:181], v[202:205], v[6:9]
	v_mfma_f32_16x16x32_bf16 v[66:69], v[158:161], v[210:213], v[66:69]
	v_mfma_f32_16x16x32_bf16 v[2:5], v[178:181], v[210:213], v[2:5]
	v_mfma_f32_16x16x32_bf16 v[86:89], v[174:177], v[190:193], v[86:89]
	v_mfma_f32_16x16x32_bf16 v[22:25], v[182:185], v[190:193], v[22:25]
	v_mfma_f32_16x16x32_bf16 v[82:85], v[174:177], v[198:201], v[82:85]
	v_mfma_f32_16x16x32_bf16 v[18:21], v[182:185], v[198:201], v[18:21]
	v_mfma_f32_16x16x32_bf16 v[70:73], v[174:177], v[206:209], v[70:73]
	v_mfma_f32_16x16x32_bf16 v[6:9], v[182:185], v[206:209], v[6:9]
	v_mfma_f32_16x16x32_bf16 v[66:69], v[174:177], v[214:217], v[66:69]
	v_mfma_f32_16x16x32_bf16 v[2:5], v[182:185], v[214:217], v[2:5]
	s_setprio 0
	s_barrier
	s_add_i32 s61, 0, 0x18000
	s_add_i32 s64, 0, 0x1c000
	v_add_u32_e32 v142, s61, v248
	v_add_u32_e32 v182, s64, v248
	ds_read_b128 v[130:133], v142
	ds_read_b128 v[134:137], v142 offset:1024
	ds_read_b128 v[138:141], v142 offset:2048
	ds_read_b128 v[142:145], v142 offset:3072
	ds_read_b128 v[158:161], v182
	ds_read_b128 v[174:177], v182 offset:1024
	ds_read_b128 v[178:181], v182 offset:2048
	ds_read_b128 v[182:185], v182 offset:3072
	s_add_u32 s94, vcc_lo, 0x80000
	s_addc_u32 s95, vcc_hi, 0
	s_mov_b32 m0, s87
	v_lshl_add_u64 v[226:227], s[94:95], 0, v[146:147]
	ds_read_b128 v[186:189], v251 offset:32768
	ds_read_b128 v[190:193], v251 offset:33792
	ds_read_b128 v[194:197], v251 offset:34816
	ds_read_b128 v[198:201], v251 offset:35840
	ds_read_b128 v[202:205], v251 offset:36864
	ds_read_b128 v[206:209], v251 offset:37888
	ds_read_b128 v[210:213], v251 offset:38912
	ds_read_b128 v[214:217], v251 offset:39936
	global_load_lds_dwordx4 v[226:227], off
	v_lshl_add_u64 v[226:227], s[94:95], 0, v[148:149]
	s_mov_b32 m0, s88
	s_nop 0
	global_load_lds_dwordx4 v[226:227], off
	s_waitcnt vmcnt(8)
	s_waitcnt lgkmcnt(0)
	s_barrier
	s_setprio 1
	s_waitcnt lgkmcnt(0)
	v_mfma_f32_16x16x32_bf16 v[126:129], v[130:133], v[186:189], v[126:129]
	v_mfma_f32_16x16x32_bf16 v[62:65], v[138:141], v[186:189], v[62:65]
	v_mfma_f32_16x16x32_bf16 v[118:121], v[130:133], v[194:197], v[118:121]
	v_mfma_f32_16x16x32_bf16 v[58:61], v[138:141], v[194:197], v[58:61]
	v_mfma_f32_16x16x32_bf16 v[110:113], v[130:133], v[202:205], v[110:113]
	v_mfma_f32_16x16x32_bf16 v[46:49], v[138:141], v[202:205], v[46:49]
	v_mfma_f32_16x16x32_bf16 v[106:109], v[130:133], v[210:213], v[106:109]
	v_mfma_f32_16x16x32_bf16 v[42:45], v[138:141], v[210:213], v[42:45]
	v_mfma_f32_16x16x32_bf16 v[126:129], v[134:137], v[190:193], v[126:129]
	v_mfma_f32_16x16x32_bf16 v[62:65], v[142:145], v[190:193], v[62:65]
	v_mfma_f32_16x16x32_bf16 v[118:121], v[134:137], v[198:201], v[118:121]
	v_mfma_f32_16x16x32_bf16 v[58:61], v[142:145], v[198:201], v[58:61]
	v_mfma_f32_16x16x32_bf16 v[110:113], v[134:137], v[206:209], v[110:113]
	v_mfma_f32_16x16x32_bf16 v[46:49], v[142:145], v[206:209], v[46:49]
	v_mfma_f32_16x16x32_bf16 v[106:109], v[134:137], v[214:217], v[106:109]
	v_mfma_f32_16x16x32_bf16 v[42:45], v[142:145], v[214:217], v[42:45]
	s_setprio 0
	s_setprio 1
	v_mfma_f32_16x16x32_bf16 v[122:125], v[158:161], v[186:189], v[122:125]
	v_mfma_f32_16x16x32_bf16 v[54:57], v[178:181], v[186:189], v[54:57]
	v_mfma_f32_16x16x32_bf16 v[114:117], v[158:161], v[194:197], v[114:117]
	v_mfma_f32_16x16x32_bf16 v[50:53], v[178:181], v[194:197], v[50:53]
	v_mfma_f32_16x16x32_bf16 v[102:105], v[158:161], v[202:205], v[102:105]
	v_mfma_f32_16x16x32_bf16 v[38:41], v[178:181], v[202:205], v[38:41]
	v_mfma_f32_16x16x32_bf16 v[98:101], v[158:161], v[210:213], v[98:101]
	v_mfma_f32_16x16x32_bf16 v[34:37], v[178:181], v[210:213], v[34:37]
	v_mfma_f32_16x16x32_bf16 v[122:125], v[174:177], v[190:193], v[122:125]
	v_mfma_f32_16x16x32_bf16 v[54:57], v[182:185], v[190:193], v[54:57]
	v_mfma_f32_16x16x32_bf16 v[114:117], v[174:177], v[198:201], v[114:117]
	v_mfma_f32_16x16x32_bf16 v[50:53], v[182:185], v[198:201], v[50:53]
	v_mfma_f32_16x16x32_bf16 v[102:105], v[174:177], v[206:209], v[102:105]
	v_mfma_f32_16x16x32_bf16 v[38:41], v[182:185], v[206:209], v[38:41]
	v_mfma_f32_16x16x32_bf16 v[98:101], v[174:177], v[214:217], v[98:101]
	v_mfma_f32_16x16x32_bf16 v[34:37], v[182:185], v[214:217], v[34:37]
	s_setprio 0
	s_barrier
; #define PG8_STAGE(bufoff, gbase, voff) do { _Pragma("unroll") for (int _i = 0; _i < 2; ++_i) \
;         __builtin_amdgcn_global_load_lds((const __attribute__((address_space(1))) unsigned*)((const char*)(gbase) + (voff)[_i]), (LAS unsigned*)(lds + (bufoff) + ldsw + _i * 8192), 16, 0, 0); } while (0)
; #define PG8_LDA(dst, b, h) do { _Pragma("unroll") for (int m = 0; m < 4; ++m) _Pragma("unroll") for (int k = 0; k < 2; ++k) dst[m][k] = *(const LAS bf16x8*)(lds + PG8_SA(b, h) + aoff + m * 2048 + k * 1024); } while (0)
; #define PG8_MMA(ai, bj, At, Bt) do { __builtin_amdgcn_s_setprio(1); _Pragma("unroll") for (int m = 0; m < 4; ++m) _Pragma("unroll") for (int n = 0; n < 2; ++n) _Pragma("unroll") for (int k = 0; k < 2; ++k) \
;         acc[ai][bj][m][n] = __builtin_amdgcn_mfma_f32_16x16x32_bf16(Bt[n][k], At[m][k], acc[ai][bj][m][n], 0, 0, 0); __builtin_amdgcn_s_setprio(0); } while (0)
; #define PG8_WAIT_V(n) asm volatile("s_waitcnt vmcnt(" #n ")" ::: "memory")
; #define PG8_WAIT_L(n) asm volatile("s_waitcnt lgkmcnt(" #n ")" ::: "memory")
; #define PG8_BAR __builtin_amdgcn_s_barrier()
; #define PG8_SCHED __builtin_amdgcn_sched_barrier(0)
; __device__ __forceinline__ float row_rstd(const float* ssp, int row, int fq) {
;     const f32x4 a = *(const f32x4*)(ssp + (size_t)row * 32 + 8 * fq), b = *(const f32x4*)(ssp + (size_t)row * 32 + 8 * fq + 4);
;     float s = ((a[0] + a[1]) + (a[2] + a[3])) + ((b[0] + b[1]) + (b[2] + b[3]));
;     s += __shfl_xor(s, 16); s += __shfl_xor(s, 32);
; template <class Epi, class SchedT, bool ALIGN_EPI, bool SP2>
; __device__ __forceinline__ void gemm_phase(LAS unsigned char* lds, const int ldk, const int nt, const SchedT& S, const Epi& E) {
;     ...
;             PG8_LDA(At, 1, 1); PG8_STAGE(PG8_SB(1, 0), b3, voffB); PG8_STAGE(PG8_SB(1, 1), b3 + hstepB, voffB); PG8_STAGE(PG8_SA(1, 0), a3, voffA);
;             PG8_WAIT_V(8); PG8_WAIT_L(0); PG8_BAR; PG8_MMA(1, 0, At, B0); PG8_MMA(1, 1, At, B1); PG8_BAR; PG8_SCHED;
	s_add_i32 s61, s61, s84
	v_lshl_add_u64 v[218:219], v[218:219], 0, s[24:25]
	s_mov_b32 m0, s61
	ds_read_b128 v[186:189], v251 offset:49152
	ds_read_b128 v[190:193], v251 offset:50176
	ds_read_b128 v[194:197], v251 offset:51200
	ds_read_b128 v[198:201], v251 offset:52224
	ds_read_b128 v[202:205], v251 offset:53248
	ds_read_b128 v[206:209], v251 offset:54272
	ds_read_b128 v[210:213], v251 offset:55296
	ds_read_b128 v[214:217], v251 offset:56320
	global_load_lds_dwordx4 v[218:219], off
	s_add_i32 m0, s61, 0x2000
	s_add_u32 s36, s36, 0x20080
	v_lshl_add_u64 v[218:219], v[220:221], 0, s[24:25]
	s_addc_u32 s37, s37, 0
	s_add_i32 s61, s64, s84
	global_load_lds_dwordx4 v[218:219], off
	v_lshl_add_u64 v[218:219], s[36:37], 0, v[0:1]
	s_mov_b32 m0, s61
	s_nop 0
	global_load_lds_dwordx4 v[218:219], off
	v_lshl_add_u64 v[218:219], s[36:37], 0, v[150:151]
	s_add_i32 m0, s61, 0x2000
	s_nop 0
	global_load_lds_dwordx4 v[218:219], off
	v_lshl_add_u64 v[218:219], v[222:223], 0, s[24:25]
	s_mov_b32 m0, s89
	s_nop 0
	global_load_lds_dwordx4 v[218:219], off
	v_lshl_add_u64 v[218:219], v[224:225], 0, s[24:25]
	s_mov_b32 m0, s90
	s_nop 0
	global_load_lds_dwordx4 v[218:219], off
	s_waitcnt vmcnt(8)
	s_waitcnt lgkmcnt(0)
	s_barrier
	s_setprio 1
	s_waitcnt lgkmcnt(0)
	v_mfma_f32_16x16x32_bf16 v[94:97], v[130:133], v[186:189], v[94:97]
	v_mfma_f32_16x16x32_bf16 v[30:33], v[138:141], v[186:189], v[30:33]
	v_mfma_f32_16x16x32_bf16 v[90:93], v[130:133], v[194:197], v[90:93]
	v_mfma_f32_16x16x32_bf16 v[26:29], v[138:141], v[194:197], v[26:29]
	v_mfma_f32_16x16x32_bf16 v[78:81], v[130:133], v[202:205], v[78:81]
	v_mfma_f32_16x16x32_bf16 v[14:17], v[138:141], v[202:205], v[14:17]
	v_mfma_f32_16x16x32_bf16 v[74:77], v[130:133], v[210:213], v[74:77]
	v_mfma_f32_16x16x32_bf16 v[10:13], v[138:141], v[210:213], v[10:13]
	v_mfma_f32_16x16x32_bf16 v[94:97], v[134:137], v[190:193], v[94:97]
	v_mfma_f32_16x16x32_bf16 v[30:33], v[142:145], v[190:193], v[30:33]
	v_mfma_f32_16x16x32_bf16 v[90:93], v[134:137], v[198:201], v[90:93]
	v_mfma_f32_16x16x32_bf16 v[26:29], v[142:145], v[198:201], v[26:29]
	v_mfma_f32_16x16x32_bf16 v[78:81], v[134:137], v[206:209], v[78:81]
	v_mfma_f32_16x16x32_bf16 v[14:17], v[142:145], v[206:209], v[14:17]
	v_mfma_f32_16x16x32_bf16 v[74:77], v[134:137], v[214:217], v[74:77]
	v_mfma_f32_16x16x32_bf16 v[10:13], v[142:145], v[214:217], v[10:13]
	s_setprio 0
	s_setprio 1
	v_mfma_f32_16x16x32_bf16 v[86:89], v[158:161], v[186:189], v[86:89]
	v_mfma_f32_16x16x32_bf16 v[22:25], v[178:181], v[186:189], v[22:25]
	v_mfma_f32_16x16x32_bf16 v[82:85], v[158:161], v[194:197], v[82:85]
	v_mfma_f32_16x16x32_bf16 v[18:21], v[178:181], v[194:197], v[18:21]
	v_mfma_f32_16x16x32_bf16 v[70:73], v[158:161], v[202:205], v[70:73]
	v_mfma_f32_16x16x32_bf16 v[6:9], v[178:181], v[202:205], v[6:9]
	v_mfma_f32_16x16x32_bf16 v[66:69], v[158:161], v[210:213], v[66:69]
	v_mfma_f32_16x16x32_bf16 v[2:5], v[178:181], v[210:213], v[2:5]
	v_mfma_f32_16x16x32_bf16 v[86:89], v[174:177], v[190:193], v[86:89]
	v_mfma_f32_16x16x32_bf16 v[22:25], v[182:185], v[190:193], v[22:25]
	v_mfma_f32_16x16x32_bf16 v[82:85], v[174:177], v[198:201], v[82:85]
	v_mfma_f32_16x16x32_bf16 v[18:21], v[182:185], v[198:201], v[18:21]
	v_mfma_f32_16x16x32_bf16 v[70:73], v[174:177], v[206:209], v[70:73]
	v_mfma_f32_16x16x32_bf16 v[6:9], v[182:185], v[206:209], v[6:9]
	v_mfma_f32_16x16x32_bf16 v[66:69], v[174:177], v[214:217], v[66:69]
	v_mfma_f32_16x16x32_bf16 v[2:5], v[182:185], v[214:217], v[2:5]
	s_setprio 0
	s_barrier
	s_add_i32 s59, s59, 2
	s_add_u32 s34, s34, 0x100
	s_addc_u32 s35, s35, 0
	s_add_u32 s13, s13, 0x100
	s_addc_u32 s17, s17, 0
	s_cmp_gt_u32 s59, 29
	s_cbranch_scc0 .LBB0_752
	v_lshl_add_u32 v130, s12, 8, v247
	v_lshlrev_b32_e32 v140, 7, v130
	v_mov_b32_e32 v141, 0
	v_lshl_add_u64 v[132:133], v[152:153], 0, v[140:141]
	v_add_u32_e32 v140, 0x1000, v140
	v_lshl_add_u64 v[134:135], v[152:153], 0, v[140:141]
	v_add_u32_e32 v140, 0x3000, v140
	v_lshl_add_u64 v[136:137], v[152:153], 0, v[140:141]
	v_add_u32_e32 v140, 0x1000, v140
	v_lshl_add_u64 v[138:139], v[152:153], 0, v[140:141]
	global_load_dwordx4 v[174:177], v[132:133], off
	global_load_dwordx4 v[178:181], v[132:133], off offset:16
	global_load_dwordx4 v[182:185], v[132:133], off offset:2048
	global_load_dwordx4 v[186:189], v[132:133], off offset:2064
	global_load_dwordx4 v[190:193], v[134:135], off
	global_load_dwordx4 v[194:197], v[134:135], off offset:16
	global_load_dwordx4 v[198:201], v[134:135], off offset:2048
	global_load_dwordx4 v[202:205], v[134:135], off offset:2064
	global_load_dwordx4 v[206:209], v[136:137], off
	global_load_dwordx4 v[210:213], v[136:137], off offset:16
	global_load_dwordx4 v[214:217], v[136:137], off offset:2048
	global_load_dwordx4 v[218:221], v[136:137], off offset:2064
	global_load_dwordx4 v[222:225], v[138:139], off
	global_load_dwordx4 v[226:229], v[138:139], off offset:16
	global_load_dwordx4 v[230:233], v[138:139], off offset:2048
	global_load_dwordx4 v[234:237], v[138:139], off offset:2064
	v_xor_b32_e32 v238, 16, v241
	v_xor_b32_e32 v239, 32, v241
	v_lshlrev_b32_e32 v238, 2, v238
	v_lshlrev_b32_e32 v239, 2, v239
	s_and_b64 vcc, exec, s[56:57]
	s_cbranch_vccz .LBB0_755
	s_barrier
